# speedup vs baseline: 1.0006x; 1.0006x over previous
; #define PG8_STAGE(bufoff, gbase, voff) do { _Pragma("unroll") for (int _i = 0; _i < 2; ++_i) \
;         __builtin_amdgcn_global_load_lds((const unsigned*)((const char*)(gbase) + (voff)[_i]), (LAS unsigned*)(lds + (bufoff) + ldsw + _i * 8192), 16, 0, 0); } while (0)
; #define PG8_LDA(dst, b, h) do { _Pragma("unroll") for (int m = 0; m < 4; ++m) _Pragma("unroll") for (int k = 0; k < 2; ++k) dst[m][k] = *(const LAS bf16x8*)(lds + PG8_SA(b, h) + aoff + m * 2048 + k * 1024); } while (0)
; #define PG8_BAR __builtin_amdgcn_s_barrier()
; template <class Epi>
; __device__ __forceinline__ void gemm_phase(const int tid, LAS unsigned char* lds, const Gemm g, const StaticOrder& S, const Epi& E) {
;     ...
;     for (;;) {
;         const bool has_next = S.next(ui + 1, nxt);
;         const char* nA = has_next ? (const char*)g.A + (size_t)nxt.pm * tstep : cA; const char* nB = has_next ? (const char*)g.Bt + (size_t)nxt.pn * tstep : cB;
;         for (int t = 0; t < nt; t += 2) {
;             const bool last = (t == nt - 2);
;             const char* a2 = last ? nA : cA + (size_t)(t + 2) * kstep; const char* b2 = last ? nB : cB + (size_t)(t + 2) * kstep;
;             const char* a3 = a2 + kstep; const char* b3 = b2 + kstep;
;             PG8_LDB(B0, 0, 0); PG8_SCHED; PG8_LDA(At, 0, 0);
;             PG8_WAIT_L(8); PG8_BAR; PG8_WAIT_L(0); PG8_MMA(0, 0, At, B0); PG8_BAR; PG8_SCHED;
;             PG8_LDB(B1, 0, 1); PG8_STAGE(PG8_SB(0, 0), b2, voffB);
;             PG8_BAR; PG8_WAIT_L(0); PG8_MMA(0, 1, At, B1); PG8_BAR;
;             PG8_LDA(At, 0, 1); PG8_STAGE(PG8_SA(0, 0), a2, voffA);
;             PG8_BAR; PG8_WAIT_L(0); PG8_MMA(1, 0, At, B0); PG8_BAR; PG8_SCHED;
;             PG8_STAGE(PG8_SB(0, 1), b2 + hstep, voffB);
;             { const int first_ = __builtin_amdgcn_readfirstlane((ui > 0 && t == 0) ? 1 : 0);
;               if constexpr (Epi::SMIN == 8) asm volatile("s_cmp_eq_u32 %0, 0\n\ts_cbranch_scc1 .Lws_a%=\n\ts_waitcnt vmcnt(14)\n\ts_branch .Lws_b%=\n.Lws_a%=:\n\ts_waitcnt vmcnt(6)\n.Lws_b%=:" :: "s"(first_) : "memory", "scc");
;               else if constexpr (Epi::SMIN == 24) asm volatile("s_cmp_eq_u32 %0, 0\n\ts_cbranch_scc1 .Lws_a%=\n\ts_waitcnt vmcnt(30)\n\ts_branch .Lws_b%=\n.Lws_a%=:\n\ts_waitcnt vmcnt(6)\n.Lws_b%=:" :: "s"(first_) : "memory", "scc");
;               else PG8_WAIT_V(6); }
;             PG8_BAR; PG8_MMA(1, 1, At, B1); PG8_BAR;
.LBB0_335:
	v_mov_b64_e32 v[2:3], 0xae0
	s_ashr_i32 s65, s64, 31
	v_cmp_lt_i64_e32 vcc, s[24:25], v[2:3]
	s_lshl_b64 s[24:25], s[64:65], 20
	s_add_u32 s60, s62, s24
	s_addc_u32 s61, s63, s25
	s_and_b64 s[24:25], vcc, exec
	s_cselect_b32 s24, s61, s11
	s_cselect_b32 s25, s60, s10
	s_ashr_i32 s23, s22, 31
	s_lshl_b64 s[48:49], s[22:23], 20
	s_add_u32 s56, s30, s48
	s_addc_u32 s57, s36, s49
	s_and_b64 s[48:49], vcc, exec
	s_cselect_b32 s23, s57, s1
	s_cselect_b32 s27, s56, s0
	s_add_u32 s28, s10, 0x100
	s_addc_u32 s39, s11, 0
	s_add_u32 s48, s0, 0x100
	s_addc_u32 s49, s1, 0
	s_mov_b32 s50, -2
	v_add_u32_e32 v243, 0x10000, v221
	v_add_u32_e32 v244, 0x14000, v221
	v_add_u32_e32 v245, 0x18000, v221
	v_add_u32_e32 v252, 0x1c000, v221
	s_add_i32 s51, 0, 0x10000
	ds_read_b128 v[130:133], v243
	ds_read_b128 v[134:137], v243 offset:1024
	ds_read_b128 v[138:141], v243 offset:2048
	ds_read_b128 v[142:145], v243 offset:3072
	s_cmp_eq_u32 s50, 28
	s_cselect_b32 s1, s24, s39
	s_cselect_b32 s0, s25, s28
	s_cselect_b32 s11, s23, s49
	s_cselect_b32 s10, s27, s48
	ds_read_b128 v[146:149], v225
	ds_read_b128 v[150:153], v225 offset:1024
	ds_read_b128 v[154:157], v225 offset:2048
	ds_read_b128 v[158:161], v225 offset:3072
	ds_read_b128 v[162:165], v225 offset:4096
	ds_read_b128 v[166:169], v225 offset:5120
	ds_read_b128 v[170:173], v225 offset:6144
	ds_read_b128 v[174:177], v225 offset:7168
	s_waitcnt lgkmcnt(8)
	s_barrier
	s_setprio 1
	s_waitcnt lgkmcnt(7)
	v_mfma_f32_16x16x32_bf16 v[126:129], v[130:133], v[146:149], 0
	v_mfma_f32_16x16x32_bf16 v[122:125], v[138:141], v[146:149], 0
	s_waitcnt lgkmcnt(5)
	v_mfma_f32_16x16x32_bf16 v[110:113], v[130:133], v[154:157], 0
	v_mfma_f32_16x16x32_bf16 v[106:109], v[138:141], v[154:157], 0
	s_waitcnt lgkmcnt(3)
	v_mfma_f32_16x16x32_bf16 v[94:97], v[130:133], v[162:165], 0
	v_mfma_f32_16x16x32_bf16 v[90:93], v[138:141], v[162:165], 0
	s_waitcnt lgkmcnt(1)
	v_mfma_f32_16x16x32_bf16 v[78:81], v[130:133], v[170:173], 0
	v_mfma_f32_16x16x32_bf16 v[74:77], v[138:141], v[170:173], 0
	v_mfma_f32_16x16x32_bf16 v[126:129], v[134:137], v[150:153], v[126:129]
	v_mfma_f32_16x16x32_bf16 v[122:125], v[142:145], v[150:153], v[122:125]
	v_mfma_f32_16x16x32_bf16 v[110:113], v[134:137], v[158:161], v[110:113]
	v_mfma_f32_16x16x32_bf16 v[106:109], v[142:145], v[158:161], v[106:109]
	v_mfma_f32_16x16x32_bf16 v[94:97], v[134:137], v[166:169], v[94:97]
	v_mfma_f32_16x16x32_bf16 v[90:93], v[142:145], v[166:169], v[90:93]
	s_waitcnt lgkmcnt(0)
	v_mfma_f32_16x16x32_bf16 v[78:81], v[134:137], v[174:177], v[78:81]
	v_mfma_f32_16x16x32_bf16 v[74:77], v[142:145], v[174:177], v[74:77]
	s_setprio 0
	s_barrier
	s_add_i32 s54, 0, 0x14000
	s_add_i32 s51, s51, s37
	s_mov_b32 m0, s51
	ds_read_b128 v[178:181], v244
	ds_read_b128 v[182:185], v244 offset:1024
	ds_read_b128 v[186:189], v244 offset:2048
	ds_read_b128 v[190:193], v244 offset:3072
	global_load_lds_dwordx4 v198, s[10:11]
	s_add_i32 m0, s51, 0x2000
	s_nop 0
	global_load_lds_dwordx4 v194, s[10:11]
	s_barrier
	s_setprio 1
	s_waitcnt lgkmcnt(3)
	v_mfma_f32_16x16x32_bf16 v[118:121], v[178:181], v[146:149], 0
	s_waitcnt lgkmcnt(1)
	v_mfma_f32_16x16x32_bf16 v[114:117], v[186:189], v[146:149], 0
	v_mfma_f32_16x16x32_bf16 v[102:105], v[178:181], v[154:157], 0
	v_mfma_f32_16x16x32_bf16 v[98:101], v[186:189], v[154:157], 0
	v_mfma_f32_16x16x32_bf16 v[86:89], v[178:181], v[162:165], 0
	v_mfma_f32_16x16x32_bf16 v[82:85], v[186:189], v[162:165], 0
	v_mfma_f32_16x16x32_bf16 v[70:73], v[178:181], v[170:173], 0
	v_mfma_f32_16x16x32_bf16 v[66:69], v[186:189], v[170:173], 0
	v_mfma_f32_16x16x32_bf16 v[118:121], v[182:185], v[150:153], v[118:121]
	s_waitcnt lgkmcnt(0)
	v_mfma_f32_16x16x32_bf16 v[114:117], v[190:193], v[150:153], v[114:117]
	v_mfma_f32_16x16x32_bf16 v[102:105], v[182:185], v[158:161], v[102:105]
	v_mfma_f32_16x16x32_bf16 v[98:101], v[190:193], v[158:161], v[98:101]
	v_mfma_f32_16x16x32_bf16 v[86:89], v[182:185], v[166:169], v[86:89]
	v_mfma_f32_16x16x32_bf16 v[82:85], v[190:193], v[166:169], v[82:85]
	v_mfma_f32_16x16x32_bf16 v[70:73], v[182:185], v[174:177], v[70:73]
	v_mfma_f32_16x16x32_bf16 v[66:69], v[190:193], v[174:177], v[66:69]
	s_setprio 0
	s_mov_b32 m0, s46
	s_barrier
	ds_read_b128 v[146:149], v225 offset:16384
	ds_read_b128 v[150:153], v225 offset:17408
	ds_read_b128 v[154:157], v225 offset:18432
	ds_read_b128 v[158:161], v225 offset:19456
	ds_read_b128 v[162:165], v225 offset:20480
	ds_read_b128 v[166:169], v225 offset:21504
	ds_read_b128 v[170:173], v225 offset:22528
	ds_read_b128 v[174:177], v225 offset:23552
	global_load_lds_dwordx4 v200, s[0:1]
	s_mov_b32 m0, s47
	s_nop 0
	global_load_lds_dwordx4 v196, s[0:1]
	s_barrier
	s_setprio 1
	s_waitcnt lgkmcnt(7)
	v_mfma_f32_16x16x32_bf16 v[62:65], v[130:133], v[146:149], 0
	v_mfma_f32_16x16x32_bf16 v[58:61], v[138:141], v[146:149], 0
	s_waitcnt lgkmcnt(5)
	v_mfma_f32_16x16x32_bf16 v[46:49], v[130:133], v[154:157], 0
	v_mfma_f32_16x16x32_bf16 v[42:45], v[138:141], v[154:157], 0
	s_waitcnt lgkmcnt(3)
	v_mfma_f32_16x16x32_bf16 v[30:33], v[130:133], v[162:165], 0
	v_mfma_f32_16x16x32_bf16 v[26:29], v[138:141], v[162:165], 0
	s_waitcnt lgkmcnt(1)
	v_mfma_f32_16x16x32_bf16 v[14:17], v[130:133], v[170:173], 0
	v_mfma_f32_16x16x32_bf16 v[10:13], v[138:141], v[170:173], 0
	v_mfma_f32_16x16x32_bf16 v[62:65], v[134:137], v[150:153], v[62:65]
	v_mfma_f32_16x16x32_bf16 v[58:61], v[142:145], v[150:153], v[58:61]
	v_mfma_f32_16x16x32_bf16 v[46:49], v[134:137], v[158:161], v[46:49]
	v_mfma_f32_16x16x32_bf16 v[42:45], v[142:145], v[158:161], v[42:45]
	v_mfma_f32_16x16x32_bf16 v[30:33], v[134:137], v[166:169], v[30:33]
	v_mfma_f32_16x16x32_bf16 v[26:29], v[142:145], v[166:169], v[26:29]
	s_waitcnt lgkmcnt(0)
	v_mfma_f32_16x16x32_bf16 v[14:17], v[134:137], v[174:177], v[14:17]
	v_mfma_f32_16x16x32_bf16 v[10:13], v[142:145], v[174:177], v[10:13]
	s_setprio 0
	s_barrier
; #define PG8_STAGE(bufoff, gbase, voff) do { _Pragma("unroll") for (int _i = 0; _i < 2; ++_i) \
;         __builtin_amdgcn_global_load_lds((const unsigned*)((const char*)(gbase) + (voff)[_i]), (LAS unsigned*)(lds + (bufoff) + ldsw + _i * 8192), 16, 0, 0); } while (0)
; #define PG8_LDA(dst, b, h) do { _Pragma("unroll") for (int m = 0; m < 4; ++m) _Pragma("unroll") for (int k = 0; k < 2; ++k) dst[m][k] = *(const LAS bf16x8*)(lds + PG8_SA(b, h) + aoff + m * 2048 + k * 1024); } while (0)
; #define PG8_LDB(dst, b, h) do { _Pragma("unroll") for (int n = 0; n < 2; ++n) _Pragma("unroll") for (int k = 0; k < 2; ++k) dst[n][k] = *(const LAS bf16x8*)(lds + PG8_SB(b, h) + boff + n * 2048 + k * 1024); } while (0)
; #define PG8_MMA(ai, bj, At, Bt) do { __builtin_amdgcn_s_setprio(1); _Pragma("unroll") for (int m = 0; m < 4; ++m) _Pragma("unroll") for (int n = 0; n < 2; ++n) _Pragma("unroll") for (int k = 0; k < 2; ++k) \
;         acc[ai][bj][m][n] = __builtin_amdgcn_mfma_f32_16x16x32_bf16(Bt[n][k], At[m][k], acc[ai][bj][m][n], 0, 0, 0); __builtin_amdgcn_s_setprio(0); } while (0)
; #define PG8_WAIT_V(n) asm volatile("s_waitcnt vmcnt(" #n ")" ::: "memory")
; #define PG8_WAIT_L(n) asm volatile("s_waitcnt lgkmcnt(" #n ")" ::: "memory")
; template <class Epi>
; __device__ __forceinline__ void gemm_phase(const int tid, LAS unsigned char* lds, const Gemm g, const StaticOrder& S, const Epi& E) {
;     ...
;             PG8_STAGE(PG8_SB(0, 1), b2 + hstep, voffB);
;             { const int first_ = __builtin_amdgcn_readfirstlane((ui > 0 && t == 0) ? 1 : 0);
;               if constexpr (Epi::SMIN == 8) asm volatile("s_cmp_eq_u32 %0, 0\n\ts_cbranch_scc1 .Lws_a%=\n\ts_waitcnt vmcnt(14)\n\ts_branch .Lws_b%=\n.Lws_a%=:\n\ts_waitcnt vmcnt(6)\n.Lws_b%=:" :: "s"(first_) : "memory", "scc");
;               else if constexpr (Epi::SMIN == 24) asm volatile("s_cmp_eq_u32 %0, 0\n\ts_cbranch_scc1 .Lws_a%=\n\ts_waitcnt vmcnt(30)\n\ts_branch .Lws_b%=\n.Lws_a%=:\n\ts_waitcnt vmcnt(6)\n.Lws_b%=:" :: "s"(first_) : "memory", "scc");
;               else PG8_WAIT_V(6); }
;             PG8_BAR; PG8_MMA(1, 1, At, B1); PG8_BAR;
;             PG8_LDB(B0, 1, 0); PG8_SCHED; PG8_LDA(At, 1, 0); PG8_STAGE(PG8_SA(0, 1), a2 + hstep, voffA);
;             PG8_WAIT_L(8); PG8_BAR; PG8_WAIT_L(0); PG8_MMA(0, 0, At, B0); PG8_BAR; PG8_SCHED;
;             PG8_LDB(B1, 1, 1); PG8_STAGE(PG8_SB(1, 0), b3, voffB);
	s_add_u32 s66, s10, 0x80000
	s_addc_u32 s67, s11, 0
	s_add_i32 s51, s54, s37
	s_mov_b32 m0, s51
	s_nop 0
	global_load_lds_dwordx4 v198, s[66:67]
	s_add_i32 m0, s51, 0x2000
	s_nop 0
	global_load_lds_dwordx4 v194, s[66:67]
	s_waitcnt vmcnt(6)
	s_barrier
	s_setprio 1
	v_mfma_f32_16x16x32_bf16 v[54:57], v[178:181], v[146:149], 0
	v_mfma_f32_16x16x32_bf16 v[50:53], v[186:189], v[146:149], 0
	v_mfma_f32_16x16x32_bf16 v[38:41], v[178:181], v[154:157], 0
	v_mfma_f32_16x16x32_bf16 v[34:37], v[186:189], v[154:157], 0
	v_mfma_f32_16x16x32_bf16 v[22:25], v[178:181], v[162:165], 0
	v_mfma_f32_16x16x32_bf16 v[18:21], v[186:189], v[162:165], 0
	v_mfma_f32_16x16x32_bf16 v[6:9], v[178:181], v[170:173], 0
	v_mfma_f32_16x16x32_bf16 v[2:5], v[186:189], v[170:173], 0
	v_mfma_f32_16x16x32_bf16 v[54:57], v[182:185], v[150:153], v[54:57]
	v_mfma_f32_16x16x32_bf16 v[50:53], v[190:193], v[150:153], v[50:53]
	v_mfma_f32_16x16x32_bf16 v[38:41], v[182:185], v[158:161], v[38:41]
	v_mfma_f32_16x16x32_bf16 v[34:37], v[190:193], v[158:161], v[34:37]
	v_mfma_f32_16x16x32_bf16 v[22:25], v[182:185], v[166:169], v[22:25]
	v_mfma_f32_16x16x32_bf16 v[18:21], v[190:193], v[166:169], v[18:21]
	v_mfma_f32_16x16x32_bf16 v[6:9], v[182:185], v[174:177], v[6:9]
	v_mfma_f32_16x16x32_bf16 v[2:5], v[190:193], v[174:177], v[2:5]
	s_setprio 0
	s_add_i32 s51, 0, 0x18000
	s_barrier
	ds_read_b128 v[130:133], v245
	ds_read_b128 v[134:137], v245 offset:1024
	ds_read_b128 v[138:141], v245 offset:2048
	ds_read_b128 v[142:145], v245 offset:3072
	s_add_u32 s66, s0, 0x80000
	s_addc_u32 s67, s1, 0
	s_mov_b32 m0, s58
	ds_read_b128 v[146:149], v225 offset:32768
	ds_read_b128 v[150:153], v225 offset:33792
	ds_read_b128 v[154:157], v225 offset:34816
	ds_read_b128 v[158:161], v225 offset:35840
	ds_read_b128 v[162:165], v225 offset:36864
	ds_read_b128 v[166:169], v225 offset:37888
	ds_read_b128 v[170:173], v225 offset:38912
	ds_read_b128 v[174:177], v225 offset:39936
	global_load_lds_dwordx4 v200, s[66:67]
	s_mov_b32 m0, s59
	s_nop 0
	global_load_lds_dwordx4 v196, s[66:67]
	s_waitcnt lgkmcnt(8)
	s_barrier
	s_setprio 1
	s_waitcnt lgkmcnt(7)
	v_mfma_f32_16x16x32_bf16 v[126:129], v[130:133], v[146:149], v[126:129]
	v_mfma_f32_16x16x32_bf16 v[122:125], v[138:141], v[146:149], v[122:125]
	s_waitcnt lgkmcnt(5)
	v_mfma_f32_16x16x32_bf16 v[110:113], v[130:133], v[154:157], v[110:113]
	v_mfma_f32_16x16x32_bf16 v[106:109], v[138:141], v[154:157], v[106:109]
	s_waitcnt lgkmcnt(3)
	v_mfma_f32_16x16x32_bf16 v[94:97], v[130:133], v[162:165], v[94:97]
	v_mfma_f32_16x16x32_bf16 v[90:93], v[138:141], v[162:165], v[90:93]
	s_waitcnt lgkmcnt(1)
	v_mfma_f32_16x16x32_bf16 v[78:81], v[130:133], v[170:173], v[78:81]
	v_mfma_f32_16x16x32_bf16 v[74:77], v[138:141], v[170:173], v[74:77]
	v_mfma_f32_16x16x32_bf16 v[126:129], v[134:137], v[150:153], v[126:129]
	v_mfma_f32_16x16x32_bf16 v[122:125], v[142:145], v[150:153], v[122:125]
	v_mfma_f32_16x16x32_bf16 v[110:113], v[134:137], v[158:161], v[110:113]
	v_mfma_f32_16x16x32_bf16 v[106:109], v[142:145], v[158:161], v[106:109]
	v_mfma_f32_16x16x32_bf16 v[94:97], v[134:137], v[166:169], v[94:97]
	v_mfma_f32_16x16x32_bf16 v[90:93], v[142:145], v[166:169], v[90:93]
	s_waitcnt lgkmcnt(0)
	v_mfma_f32_16x16x32_bf16 v[78:81], v[134:137], v[174:177], v[78:81]
	v_mfma_f32_16x16x32_bf16 v[74:77], v[142:145], v[174:177], v[74:77]
	s_setprio 0
	s_barrier
	s_add_i32 s54, 0, 0x1c000
	s_add_i32 s51, s51, s37
	s_add_i32 m0, s51, 0xffffff80
	ds_read_b128 v[178:181], v252
	ds_read_b128 v[182:185], v252 offset:1024
	ds_read_b128 v[186:189], v252 offset:2048
	ds_read_b128 v[190:193], v252 offset:3072
	global_load_lds_dwordx4 v198, s[10:11] offset:128
	s_add_i32 m0, s51, 0x1f80
	s_nop 0
	global_load_lds_dwordx4 v194, s[10:11] offset:128
	s_barrier
; #define PG8_STAGE(bufoff, gbase, voff) do { _Pragma("unroll") for (int _i = 0; _i < 2; ++_i) \
;         __builtin_amdgcn_global_load_lds((const unsigned*)((const char*)(gbase) + (voff)[_i]), (LAS unsigned*)(lds + (bufoff) + ldsw + _i * 8192), 16, 0, 0); } while (0)
; #define PG8_LDA(dst, b, h) do { _Pragma("unroll") for (int m = 0; m < 4; ++m) _Pragma("unroll") for (int k = 0; k < 2; ++k) dst[m][k] = *(const LAS bf16x8*)(lds + PG8_SA(b, h) + aoff + m * 2048 + k * 1024); } while (0)
; #define PG8_MMA(ai, bj, At, Bt) do { __builtin_amdgcn_s_setprio(1); _Pragma("unroll") for (int m = 0; m < 4; ++m) _Pragma("unroll") for (int n = 0; n < 2; ++n) _Pragma("unroll") for (int k = 0; k < 2; ++k) \
;         acc[ai][bj][m][n] = __builtin_amdgcn_mfma_f32_16x16x32_bf16(Bt[n][k], At[m][k], acc[ai][bj][m][n], 0, 0, 0); __builtin_amdgcn_s_setprio(0); } while (0)
; #define PG8_WAIT_V(n) asm volatile("s_waitcnt vmcnt(" #n ")" ::: "memory")
; #define PG8_WAIT_L(n) asm volatile("s_waitcnt lgkmcnt(" #n ")" ::: "memory")
; #define PG8_BAR __builtin_amdgcn_s_barrier()
; #define PG8_SCHED __builtin_amdgcn_sched_barrier(0)
; template <class Epi>
; __device__ __forceinline__ void gemm_phase(const int tid, LAS unsigned char* lds, const Gemm g, const StaticOrder& S, const Epi& E) {
;     ...
;             PG8_BAR; PG8_WAIT_L(0); PG8_MMA(0, 1, At, B1); PG8_BAR;
;             PG8_LDA(At, 1, 1); PG8_STAGE(PG8_SA(1, 0), a3, voffA);
;             PG8_BAR; PG8_WAIT_L(0); PG8_MMA(1, 0, At, B0); PG8_BAR; PG8_SCHED;
;             PG8_STAGE(PG8_SB(1, 1), b3 + hstep, voffB);
;             PG8_WAIT_V(6); PG8_BAR; PG8_STAGE(PG8_SA(1, 1), a3 + hstep, voffA);
;             PG8_MMA(1, 1, At, B1); PG8_BAR;
	s_setprio 1
	s_waitcnt lgkmcnt(3)
	v_mfma_f32_16x16x32_bf16 v[118:121], v[178:181], v[146:149], v[118:121]
	s_waitcnt lgkmcnt(1)
	v_mfma_f32_16x16x32_bf16 v[114:117], v[186:189], v[146:149], v[114:117]
	v_mfma_f32_16x16x32_bf16 v[102:105], v[178:181], v[154:157], v[102:105]
	v_mfma_f32_16x16x32_bf16 v[98:101], v[186:189], v[154:157], v[98:101]
	v_mfma_f32_16x16x32_bf16 v[86:89], v[178:181], v[162:165], v[86:89]
	v_mfma_f32_16x16x32_bf16 v[82:85], v[186:189], v[162:165], v[82:85]
	v_mfma_f32_16x16x32_bf16 v[70:73], v[178:181], v[170:173], v[70:73]
	v_mfma_f32_16x16x32_bf16 v[66:69], v[186:189], v[170:173], v[66:69]
	v_mfma_f32_16x16x32_bf16 v[118:121], v[182:185], v[150:153], v[118:121]
	s_waitcnt lgkmcnt(0)
	v_mfma_f32_16x16x32_bf16 v[114:117], v[190:193], v[150:153], v[114:117]
	v_mfma_f32_16x16x32_bf16 v[102:105], v[182:185], v[158:161], v[102:105]
	v_mfma_f32_16x16x32_bf16 v[98:101], v[190:193], v[158:161], v[98:101]
	v_mfma_f32_16x16x32_bf16 v[86:89], v[182:185], v[166:169], v[86:89]
	v_mfma_f32_16x16x32_bf16 v[82:85], v[190:193], v[166:169], v[82:85]
	v_mfma_f32_16x16x32_bf16 v[70:73], v[182:185], v[174:177], v[70:73]
	v_mfma_f32_16x16x32_bf16 v[66:69], v[190:193], v[174:177], v[66:69]
	s_setprio 0
	s_add_i32 m0, s68, 0xffffff80
	s_barrier
	ds_read_b128 v[146:149], v225 offset:49152
	ds_read_b128 v[150:153], v225 offset:50176
	ds_read_b128 v[154:157], v225 offset:51200
	ds_read_b128 v[158:161], v225 offset:52224
	ds_read_b128 v[162:165], v225 offset:53248
	ds_read_b128 v[166:169], v225 offset:54272
	ds_read_b128 v[170:173], v225 offset:55296
	ds_read_b128 v[174:177], v225 offset:56320
	global_load_lds_dwordx4 v200, s[0:1] offset:128
	s_add_i32 m0, s69, 0xffffff80
	s_nop 0
	global_load_lds_dwordx4 v196, s[0:1] offset:128
	s_barrier
	s_setprio 1
	s_waitcnt lgkmcnt(7)
	v_mfma_f32_16x16x32_bf16 v[62:65], v[130:133], v[146:149], v[62:65]
	v_mfma_f32_16x16x32_bf16 v[58:61], v[138:141], v[146:149], v[58:61]
	s_waitcnt lgkmcnt(5)
	v_mfma_f32_16x16x32_bf16 v[46:49], v[130:133], v[154:157], v[46:49]
	v_mfma_f32_16x16x32_bf16 v[42:45], v[138:141], v[154:157], v[42:45]
	s_waitcnt lgkmcnt(3)
	v_mfma_f32_16x16x32_bf16 v[30:33], v[130:133], v[162:165], v[30:33]
	v_mfma_f32_16x16x32_bf16 v[26:29], v[138:141], v[162:165], v[26:29]
	s_waitcnt lgkmcnt(1)
	v_mfma_f32_16x16x32_bf16 v[14:17], v[130:133], v[170:173], v[14:17]
	v_mfma_f32_16x16x32_bf16 v[10:13], v[138:141], v[170:173], v[10:13]
	v_mfma_f32_16x16x32_bf16 v[62:65], v[134:137], v[150:153], v[62:65]
	v_mfma_f32_16x16x32_bf16 v[58:61], v[142:145], v[150:153], v[58:61]
	v_mfma_f32_16x16x32_bf16 v[46:49], v[134:137], v[158:161], v[46:49]
	v_mfma_f32_16x16x32_bf16 v[42:45], v[142:145], v[158:161], v[42:45]
	v_mfma_f32_16x16x32_bf16 v[30:33], v[134:137], v[166:169], v[30:33]
	v_mfma_f32_16x16x32_bf16 v[26:29], v[142:145], v[166:169], v[26:29]
	s_waitcnt lgkmcnt(0)
	v_mfma_f32_16x16x32_bf16 v[14:17], v[134:137], v[174:177], v[14:17]
	v_mfma_f32_16x16x32_bf16 v[10:13], v[142:145], v[174:177], v[10:13]
	s_setprio 0
	s_barrier
	s_add_u32 s10, s10, 0x80080
	s_addc_u32 s11, s11, 0
	s_add_i32 s51, s54, s37
	s_mov_b32 m0, s51
	s_nop 0
	global_load_lds_dwordx4 v198, s[10:11]
	s_add_i32 m0, s51, 0x2000
	s_add_u32 s0, s0, 0x80080
	s_addc_u32 s1, s1, 0
	global_load_lds_dwordx4 v194, s[10:11]
	s_mov_b32 m0, s84
	s_waitcnt vmcnt(6)
	s_barrier
	global_load_lds_dwordx4 v200, s[0:1]
	s_mov_b32 m0, s85
	s_nop 0
	global_load_lds_dwordx4 v196, s[0:1]
	s_setprio 1
	v_mfma_f32_16x16x32_bf16 v[54:57], v[178:181], v[146:149], v[54:57]
	v_mfma_f32_16x16x32_bf16 v[50:53], v[186:189], v[146:149], v[50:53]
	v_mfma_f32_16x16x32_bf16 v[38:41], v[178:181], v[154:157], v[38:41]
	v_mfma_f32_16x16x32_bf16 v[34:37], v[186:189], v[154:157], v[34:37]
	v_mfma_f32_16x16x32_bf16 v[22:25], v[178:181], v[162:165], v[22:25]
	v_mfma_f32_16x16x32_bf16 v[18:21], v[186:189], v[162:165], v[18:21]
	v_mfma_f32_16x16x32_bf16 v[6:9], v[178:181], v[170:173], v[6:9]
	v_mfma_f32_16x16x32_bf16 v[2:5], v[186:189], v[170:173], v[2:5]
	v_mfma_f32_16x16x32_bf16 v[54:57], v[182:185], v[150:153], v[54:57]
	v_mfma_f32_16x16x32_bf16 v[50:53], v[190:193], v[150:153], v[50:53]
	v_mfma_f32_16x16x32_bf16 v[38:41], v[182:185], v[158:161], v[38:41]
	v_mfma_f32_16x16x32_bf16 v[34:37], v[190:193], v[158:161], v[34:37]
	v_mfma_f32_16x16x32_bf16 v[22:25], v[182:185], v[166:169], v[22:25]
	v_mfma_f32_16x16x32_bf16 v[18:21], v[190:193], v[166:169], v[18:21]
	v_mfma_f32_16x16x32_bf16 v[6:9], v[182:185], v[174:177], v[6:9]
	v_mfma_f32_16x16x32_bf16 v[2:5], v[190:193], v[174:177], v[2:5]
	s_setprio 0
	s_add_i32 s50, s50, 2
	s_add_u32 s28, s28, 0x100
	s_addc_u32 s39, s39, 0
	s_add_u32 s48, s48, 0x100
	s_addc_u32 s49, s49, 0
	s_cmp_gt_u32 s50, 29
	s_barrier

; #define PG8_STAGE(bufoff, gbase, voff) do { _Pragma("unroll") for (int _i = 0; _i < 2; ++_i) \
;         __builtin_amdgcn_global_load_lds((const unsigned*)((const char*)(gbase) + (voff)[_i]), (LAS unsigned*)(lds + (bufoff) + ldsw + _i * 8192), 16, 0, 0); } while (0)
; #define PG8_LDA(dst, b, h) do { _Pragma("unroll") for (int m = 0; m < 4; ++m) _Pragma("unroll") for (int k = 0; k < 2; ++k) dst[m][k] = *(const LAS bf16x8*)(lds + PG8_SA(b, h) + aoff + m * 2048 + k * 1024); } while (0)
; #define PG8_WAIT_V(n) asm volatile("s_waitcnt vmcnt(" #n ")" ::: "memory")
; template <class Epi>
; __device__ __forceinline__ void gemm_phase(const int tid, LAS unsigned char* lds, const Gemm g, const StaticOrder& S, const Epi& E) {
;     ...
;     for (;;) {
;         const bool has_next = S.next(ui + 1, nxt);
;         const char* nA = has_next ? (const char*)g.A + (size_t)nxt.pm * tstep : cA; const char* nB = has_next ? (const char*)g.Bt + (size_t)nxt.pn * tstep : cB;
;         for (int t = 0; t < nt; t += 2) {
;             const bool last = (t == nt - 2);
;             const char* a2 = last ? nA : cA + (size_t)(t + 2) * kstep; const char* b2 = last ? nB : cB + (size_t)(t + 2) * kstep;
;             const char* a3 = a2 + kstep; const char* b3 = b2 + kstep;
;             PG8_LDB(B0, 0, 0); PG8_SCHED; PG8_LDA(At, 0, 0);
;             PG8_WAIT_L(8); PG8_BAR; PG8_WAIT_L(0); PG8_MMA(0, 0, At, B0); PG8_BAR; PG8_SCHED;
;             PG8_LDB(B1, 0, 1); PG8_STAGE(PG8_SB(0, 0), b2, voffB);
;             PG8_BAR; PG8_WAIT_L(0); PG8_MMA(0, 1, At, B1); PG8_BAR;
;             PG8_LDA(At, 0, 1); PG8_STAGE(PG8_SA(0, 0), a2, voffA);
;             PG8_BAR; PG8_WAIT_L(0); PG8_MMA(1, 0, At, B0); PG8_BAR; PG8_SCHED;
;             PG8_STAGE(PG8_SB(0, 1), b2 + hstep, voffB);
;             { const int first_ = __builtin_amdgcn_readfirstlane((ui > 0 && t == 0) ? 1 : 0);
;               if constexpr (Epi::SMIN == 8) asm volatile("s_cmp_eq_u32 %0, 0\n\ts_cbranch_scc1 .Lws_a%=\n\ts_waitcnt vmcnt(14)\n\ts_branch .Lws_b%=\n.Lws_a%=:\n\ts_waitcnt vmcnt(6)\n.Lws_b%=:" :: "s"(first_) : "memory", "scc");
;               else if constexpr (Epi::SMIN == 24) asm volatile("s_cmp_eq_u32 %0, 0\n\ts_cbranch_scc1 .Lws_a%=\n\ts_waitcnt vmcnt(30)\n\ts_branch .Lws_b%=\n.Lws_a%=:\n\ts_waitcnt vmcnt(6)\n.Lws_b%=:" :: "s"(first_) : "memory", "scc");
;               else PG8_WAIT_V(6); }
.LBB0_418:
	s_cmp_lg_u32 s12, 0
	s_cselect_b64 s[12:13], -1, 0
	s_add_u32 s60, s16, 0x100
	s_addc_u32 s61, s17, 0
	s_add_u32 s64, s14, 0x100
	s_mov_b32 s66, 0
	s_addc_u32 s65, s15, 0
	v_add_u32_e32 v243, 0x10000, v246
	v_add_u32_e32 v244, 0x14000, v246
	v_add_u32_e32 v249, 0x18000, v246
	v_add_u32_e32 v250, 0x1c000, v246
	s_add_i32 s68, 0, 0x10000
	ds_read_b128 v[106:109], v243
	ds_read_b128 v[110:113], v243 offset:1024
	ds_read_b128 v[122:125], v243 offset:2048
	ds_read_b128 v[134:137], v243 offset:3072
	s_add_i32 s67, s66, 2
	s_cmp_eq_u32 s54, s66
	s_cselect_b32 s15, s9, s61
	s_cselect_b32 s14, s8, s60
	s_cselect_b32 s17, s11, s65
	s_cselect_b32 s16, s10, s64
	ds_read_b128 v[138:141], v248
	ds_read_b128 v[142:145], v248 offset:1024
	ds_read_b128 v[146:149], v248 offset:2048
	ds_read_b128 v[150:153], v248 offset:3072
	ds_read_b128 v[154:157], v248 offset:4096
	ds_read_b128 v[158:161], v248 offset:5120
	ds_read_b128 v[162:165], v248 offset:6144
	ds_read_b128 v[174:177], v248 offset:7168
	s_waitcnt lgkmcnt(8)
	s_barrier
	s_setprio 1
	s_waitcnt lgkmcnt(7)
	v_mfma_f32_16x16x32_bf16 v[170:173], v[106:109], v[138:141], 0
	v_mfma_f32_16x16x32_bf16 v[166:169], v[122:125], v[138:141], 0
	s_waitcnt lgkmcnt(5)
	v_mfma_f32_16x16x32_bf16 v[118:121], v[106:109], v[146:149], 0
	v_mfma_f32_16x16x32_bf16 v[114:117], v[122:125], v[146:149], 0
	s_waitcnt lgkmcnt(3)
	v_mfma_f32_16x16x32_bf16 v[94:97], v[106:109], v[154:157], 0
	v_mfma_f32_16x16x32_bf16 v[90:93], v[122:125], v[154:157], 0
	s_waitcnt lgkmcnt(1)
	v_mfma_f32_16x16x32_bf16 v[78:81], v[106:109], v[162:165], 0
	v_mfma_f32_16x16x32_bf16 v[74:77], v[122:125], v[162:165], 0
	v_mfma_f32_16x16x32_bf16 v[170:173], v[110:113], v[142:145], v[170:173]
	v_mfma_f32_16x16x32_bf16 v[166:169], v[134:137], v[142:145], v[166:169]
	v_mfma_f32_16x16x32_bf16 v[118:121], v[110:113], v[150:153], v[118:121]
	v_mfma_f32_16x16x32_bf16 v[114:117], v[134:137], v[150:153], v[114:117]
	v_mfma_f32_16x16x32_bf16 v[94:97], v[110:113], v[158:161], v[94:97]
	v_mfma_f32_16x16x32_bf16 v[90:93], v[134:137], v[158:161], v[90:93]
	s_waitcnt lgkmcnt(0)
	v_mfma_f32_16x16x32_bf16 v[78:81], v[110:113], v[174:177], v[78:81]
	v_mfma_f32_16x16x32_bf16 v[74:77], v[134:137], v[174:177], v[74:77]
	s_setprio 0
	s_barrier
	s_add_i32 s69, 0, 0x14000
	s_add_i32 s68, s68, s28
	s_mov_b32 m0, s68
	ds_read_b128 v[178:181], v244
	ds_read_b128 v[182:185], v244 offset:1024
	ds_read_b128 v[186:189], v244 offset:2048
	ds_read_b128 v[190:193], v244 offset:3072
	global_load_lds_dwordx4 v0, s[16:17]
	s_add_i32 m0, s68, 0x2000
	s_nop 0
	global_load_lds_dwordx4 v194, s[16:17]
	s_barrier
	s_setprio 1
	s_waitcnt lgkmcnt(3)
	v_mfma_f32_16x16x32_bf16 v[130:133], v[178:181], v[138:141], 0
	s_waitcnt lgkmcnt(1)
	v_mfma_f32_16x16x32_bf16 v[126:129], v[186:189], v[138:141], 0
	v_mfma_f32_16x16x32_bf16 v[102:105], v[178:181], v[146:149], 0
	v_mfma_f32_16x16x32_bf16 v[98:101], v[186:189], v[146:149], 0
	v_mfma_f32_16x16x32_bf16 v[86:89], v[178:181], v[154:157], 0
	v_mfma_f32_16x16x32_bf16 v[82:85], v[186:189], v[154:157], 0
	v_mfma_f32_16x16x32_bf16 v[70:73], v[178:181], v[162:165], 0
	v_mfma_f32_16x16x32_bf16 v[66:69], v[186:189], v[162:165], 0
	v_mfma_f32_16x16x32_bf16 v[130:133], v[182:185], v[142:145], v[130:133]
	s_waitcnt lgkmcnt(0)
	v_mfma_f32_16x16x32_bf16 v[126:129], v[190:193], v[142:145], v[126:129]
	v_mfma_f32_16x16x32_bf16 v[102:105], v[182:185], v[150:153], v[102:105]
	v_mfma_f32_16x16x32_bf16 v[98:101], v[190:193], v[150:153], v[98:101]
	v_mfma_f32_16x16x32_bf16 v[86:89], v[182:185], v[158:161], v[86:89]
	v_mfma_f32_16x16x32_bf16 v[82:85], v[190:193], v[158:161], v[82:85]
	v_mfma_f32_16x16x32_bf16 v[70:73], v[182:185], v[174:177], v[70:73]
	v_mfma_f32_16x16x32_bf16 v[66:69], v[190:193], v[174:177], v[66:69]
	s_setprio 0
	s_mov_b32 m0, s36
	s_barrier
	ds_read_b128 v[138:141], v248 offset:16384
	ds_read_b128 v[142:145], v248 offset:17408
	ds_read_b128 v[146:149], v248 offset:18432
	ds_read_b128 v[150:153], v248 offset:19456
	ds_read_b128 v[154:157], v248 offset:20480
	ds_read_b128 v[158:161], v248 offset:21504
	ds_read_b128 v[162:165], v248 offset:22528
	ds_read_b128 v[174:177], v248 offset:23552
	global_load_lds_dwordx4 v198, s[14:15]
	s_mov_b32 m0, s37
	s_nop 0
	global_load_lds_dwordx4 v196, s[14:15]
	s_barrier
	s_setprio 1
	s_waitcnt lgkmcnt(7)
	v_mfma_f32_16x16x32_bf16 v[62:65], v[106:109], v[138:141], 0
	v_mfma_f32_16x16x32_bf16 v[58:61], v[122:125], v[138:141], 0
	s_waitcnt lgkmcnt(5)
	v_mfma_f32_16x16x32_bf16 v[46:49], v[106:109], v[146:149], 0
	v_mfma_f32_16x16x32_bf16 v[42:45], v[122:125], v[146:149], 0
	s_waitcnt lgkmcnt(3)
	v_mfma_f32_16x16x32_bf16 v[30:33], v[106:109], v[154:157], 0
	v_mfma_f32_16x16x32_bf16 v[26:29], v[122:125], v[154:157], 0
	s_waitcnt lgkmcnt(1)
	v_mfma_f32_16x16x32_bf16 v[14:17], v[106:109], v[162:165], 0
	v_mfma_f32_16x16x32_bf16 v[10:13], v[122:125], v[162:165], 0
	v_mfma_f32_16x16x32_bf16 v[62:65], v[110:113], v[142:145], v[62:65]
	v_mfma_f32_16x16x32_bf16 v[58:61], v[134:137], v[142:145], v[58:61]
	v_mfma_f32_16x16x32_bf16 v[46:49], v[110:113], v[150:153], v[46:49]
	v_mfma_f32_16x16x32_bf16 v[42:45], v[134:137], v[150:153], v[42:45]
	v_mfma_f32_16x16x32_bf16 v[30:33], v[110:113], v[158:161], v[30:33]
	v_mfma_f32_16x16x32_bf16 v[26:29], v[134:137], v[158:161], v[26:29]
	s_waitcnt lgkmcnt(0)
	v_mfma_f32_16x16x32_bf16 v[14:17], v[110:113], v[174:177], v[14:17]
	v_mfma_f32_16x16x32_bf16 v[10:13], v[134:137], v[174:177], v[10:13]
	s_setprio 0
	s_barrier
	s_add_u32 s16, s16, s26
	s_addc_u32 s17, s17, 0
	s_add_i32 s68, s69, s28
	s_mov_b32 m0, s68
	s_nop 0
	global_load_lds_dwordx4 v0, s[16:17]
	s_add_i32 m0, s68, 0x2000
	s_cmp_eq_u32 s66, 0
	global_load_lds_dwordx4 v194, s[16:17]
	s_cselect_b64 s[16:17], -1, 0
	s_and_b64 s[16:17], s[12:13], s[16:17]
	v_cndmask_b32_e64 v106, 0, 1, s[16:17]
	s_nop 0
	v_readfirstlane_b32 s16, v106
	s_and_b32 s16, s16, 1
	s_cmp_eq_u32 s16, 0
	s_cbranch_scc1 .Lws_a0_pl
	s_waitcnt vmcnt(30)
	s_branch .Lws_b0_pl

; #define PG8_STAGE(bufoff, gbase, voff) do { _Pragma("unroll") for (int _i = 0; _i < 2; ++_i) \
;         __builtin_amdgcn_global_load_lds((const unsigned*)((const char*)(gbase) + (voff)[_i]), (LAS unsigned*)(lds + (bufoff) + ldsw + _i * 8192), 16, 0, 0); } while (0)
; #define PG8_LDA(dst, b, h) do { _Pragma("unroll") for (int m = 0; m < 4; ++m) _Pragma("unroll") for (int k = 0; k < 2; ++k) dst[m][k] = *(const LAS bf16x8*)(lds + PG8_SA(b, h) + aoff + m * 2048 + k * 1024); } while (0)
; #define PG8_LDB(dst, b, h) do { _Pragma("unroll") for (int n = 0; n < 2; ++n) _Pragma("unroll") for (int k = 0; k < 2; ++k) dst[n][k] = *(const LAS bf16x8*)(lds + PG8_SB(b, h) + boff + n * 2048 + k * 1024); } while (0)
; #define PG8_MMA(ai, bj, At, Bt) do { __builtin_amdgcn_s_setprio(1); _Pragma("unroll") for (int m = 0; m < 4; ++m) _Pragma("unroll") for (int n = 0; n < 2; ++n) _Pragma("unroll") for (int k = 0; k < 2; ++k) \
;         acc[ai][bj][m][n] = __builtin_amdgcn_mfma_f32_16x16x32_bf16(Bt[n][k], At[m][k], acc[ai][bj][m][n], 0, 0, 0); __builtin_amdgcn_s_setprio(0); } while (0)
; #define PG8_WAIT_L(n) asm volatile("s_waitcnt lgkmcnt(" #n ")" ::: "memory")
; #define PG8_BAR __builtin_amdgcn_s_barrier()
; #define PG8_SCHED __builtin_amdgcn_sched_barrier(0)
; template <class Epi>
; __device__ __forceinline__ void gemm_phase(const int tid, LAS unsigned char* lds, const Gemm g, const StaticOrder& S, const Epi& E) {
;     ...
;             PG8_BAR; PG8_MMA(1, 1, At, B1); PG8_BAR;
;             PG8_LDB(B0, 1, 0); PG8_SCHED; PG8_LDA(At, 1, 0); PG8_STAGE(PG8_SA(0, 1), a2 + hstep, voffA);
;             PG8_WAIT_L(8); PG8_BAR; PG8_WAIT_L(0); PG8_MMA(0, 0, At, B0); PG8_BAR; PG8_SCHED;
;             PG8_LDB(B1, 1, 1); PG8_STAGE(PG8_SB(1, 0), b3, voffB);
;             PG8_BAR; PG8_WAIT_L(0); PG8_MMA(0, 1, At, B1); PG8_BAR;
;             PG8_LDA(At, 1, 1); PG8_STAGE(PG8_SA(1, 0), a3, voffA);
;             PG8_BAR; PG8_WAIT_L(0); PG8_MMA(1, 0, At, B0); PG8_BAR; PG8_SCHED;
.Lws_b0_pl:
	s_barrier
	s_setprio 1
	v_mfma_f32_16x16x32_bf16 v[54:57], v[178:181], v[138:141], 0
	v_mfma_f32_16x16x32_bf16 v[50:53], v[186:189], v[138:141], 0
	v_mfma_f32_16x16x32_bf16 v[38:41], v[178:181], v[146:149], 0
	v_mfma_f32_16x16x32_bf16 v[34:37], v[186:189], v[146:149], 0
	v_mfma_f32_16x16x32_bf16 v[22:25], v[178:181], v[154:157], 0
	v_mfma_f32_16x16x32_bf16 v[18:21], v[186:189], v[154:157], 0
	v_mfma_f32_16x16x32_bf16 v[6:9], v[178:181], v[162:165], 0
	v_mfma_f32_16x16x32_bf16 v[2:5], v[186:189], v[162:165], 0
	v_mfma_f32_16x16x32_bf16 v[54:57], v[182:185], v[142:145], v[54:57]
	v_mfma_f32_16x16x32_bf16 v[50:53], v[190:193], v[142:145], v[50:53]
	v_mfma_f32_16x16x32_bf16 v[38:41], v[182:185], v[150:153], v[38:41]
	v_mfma_f32_16x16x32_bf16 v[34:37], v[190:193], v[150:153], v[34:37]
	v_mfma_f32_16x16x32_bf16 v[22:25], v[182:185], v[158:161], v[22:25]
	v_mfma_f32_16x16x32_bf16 v[18:21], v[190:193], v[158:161], v[18:21]
	v_mfma_f32_16x16x32_bf16 v[6:9], v[182:185], v[174:177], v[6:9]
	v_mfma_f32_16x16x32_bf16 v[2:5], v[190:193], v[174:177], v[2:5]
	s_setprio 0
	s_add_i32 s16, 0, 0x18000
	s_barrier
	ds_read_b128 v[106:109], v249
	ds_read_b128 v[110:113], v249 offset:1024
	ds_read_b128 v[122:125], v249 offset:2048
	ds_read_b128 v[134:137], v249 offset:3072
	s_add_u32 s14, s14, s26
	s_addc_u32 s15, s15, 0
	s_mov_b32 m0, s38
	ds_read_b128 v[138:141], v248 offset:32768
	ds_read_b128 v[142:145], v248 offset:33792
	ds_read_b128 v[146:149], v248 offset:34816
	ds_read_b128 v[150:153], v248 offset:35840
	ds_read_b128 v[154:157], v248 offset:36864
	ds_read_b128 v[158:161], v248 offset:37888
	ds_read_b128 v[162:165], v248 offset:38912
	ds_read_b128 v[174:177], v248 offset:39936
	global_load_lds_dwordx4 v198, s[14:15]
	s_mov_b32 m0, s39
	s_nop 0
	global_load_lds_dwordx4 v196, s[14:15]
	s_waitcnt lgkmcnt(8)
	s_barrier
	s_setprio 1
	s_waitcnt lgkmcnt(7)
	v_mfma_f32_16x16x32_bf16 v[170:173], v[106:109], v[138:141], v[170:173]
	v_mfma_f32_16x16x32_bf16 v[166:169], v[122:125], v[138:141], v[166:169]
	s_waitcnt lgkmcnt(5)
	v_mfma_f32_16x16x32_bf16 v[118:121], v[106:109], v[146:149], v[118:121]
	v_mfma_f32_16x16x32_bf16 v[114:117], v[122:125], v[146:149], v[114:117]
	s_waitcnt lgkmcnt(3)
	v_mfma_f32_16x16x32_bf16 v[94:97], v[106:109], v[154:157], v[94:97]
	v_mfma_f32_16x16x32_bf16 v[90:93], v[122:125], v[154:157], v[90:93]
	s_waitcnt lgkmcnt(1)
	v_mfma_f32_16x16x32_bf16 v[78:81], v[106:109], v[162:165], v[78:81]
	v_mfma_f32_16x16x32_bf16 v[74:77], v[122:125], v[162:165], v[74:77]
	v_mfma_f32_16x16x32_bf16 v[170:173], v[110:113], v[142:145], v[170:173]
	v_mfma_f32_16x16x32_bf16 v[166:169], v[134:137], v[142:145], v[166:169]
	v_mfma_f32_16x16x32_bf16 v[118:121], v[110:113], v[150:153], v[118:121]
	v_mfma_f32_16x16x32_bf16 v[114:117], v[134:137], v[150:153], v[114:117]
	v_mfma_f32_16x16x32_bf16 v[94:97], v[110:113], v[158:161], v[94:97]
	v_mfma_f32_16x16x32_bf16 v[90:93], v[134:137], v[158:161], v[90:93]
	s_waitcnt lgkmcnt(0)
	v_mfma_f32_16x16x32_bf16 v[78:81], v[110:113], v[174:177], v[78:81]
	v_mfma_f32_16x16x32_bf16 v[74:77], v[134:137], v[174:177], v[74:77]
	s_setprio 0
	s_barrier
	s_add_i32 s14, 0, 0x1c000
	s_add_i32 s15, s16, s28
	s_cmp_eq_u32 s54, s66
	s_cselect_b32 s17, s11, s65
	s_cselect_b32 s16, s10, s64
	s_cselect_b32 s69, s9, s61
	s_cselect_b32 s68, s8, s60
	s_add_i32 m0, s15, 0xffffff80
	ds_read_b128 v[178:181], v250
	ds_read_b128 v[182:185], v250 offset:1024
	ds_read_b128 v[186:189], v250 offset:2048
	ds_read_b128 v[190:193], v250 offset:3072
	global_load_lds_dwordx4 v0, s[16:17] offset:128
	s_add_i32 m0, s15, 0x1f80
	s_nop 0
	global_load_lds_dwordx4 v194, s[16:17] offset:128
	s_barrier
; #define PG8_STAGE(bufoff, gbase, voff) do { _Pragma("unroll") for (int _i = 0; _i < 2; ++_i) \
;         __builtin_amdgcn_global_load_lds((const unsigned*)((const char*)(gbase) + (voff)[_i]), (LAS unsigned*)(lds + (bufoff) + ldsw + _i * 8192), 16, 0, 0); } while (0)
; #define PG8_LDA(dst, b, h) do { _Pragma("unroll") for (int m = 0; m < 4; ++m) _Pragma("unroll") for (int k = 0; k < 2; ++k) dst[m][k] = *(const LAS bf16x8*)(lds + PG8_SA(b, h) + aoff + m * 2048 + k * 1024); } while (0)
; #define PG8_MMA(ai, bj, At, Bt) do { __builtin_amdgcn_s_setprio(1); _Pragma("unroll") for (int m = 0; m < 4; ++m) _Pragma("unroll") for (int n = 0; n < 2; ++n) _Pragma("unroll") for (int k = 0; k < 2; ++k) \
;         acc[ai][bj][m][n] = __builtin_amdgcn_mfma_f32_16x16x32_bf16(Bt[n][k], At[m][k], acc[ai][bj][m][n], 0, 0, 0); __builtin_amdgcn_s_setprio(0); } while (0)
; #define PG8_WAIT_V(n) asm volatile("s_waitcnt vmcnt(" #n ")" ::: "memory")
; #define PG8_WAIT_L(n) asm volatile("s_waitcnt lgkmcnt(" #n ")" ::: "memory")
; #define PG8_BAR __builtin_amdgcn_s_barrier()
; #define PG8_SCHED __builtin_amdgcn_sched_barrier(0)
; template <class Epi>
; __device__ __forceinline__ void gemm_phase(const int tid, LAS unsigned char* lds, const Gemm g, const StaticOrder& S, const Epi& E) {
;     ...
;             PG8_BAR; PG8_WAIT_L(0); PG8_MMA(0, 1, At, B1); PG8_BAR;
;             PG8_LDA(At, 1, 1); PG8_STAGE(PG8_SA(1, 0), a3, voffA);
;             PG8_BAR; PG8_WAIT_L(0); PG8_MMA(1, 0, At, B0); PG8_BAR; PG8_SCHED;
;             PG8_STAGE(PG8_SB(1, 1), b3 + hstep, voffB);
;             PG8_WAIT_V(6); PG8_BAR; PG8_STAGE(PG8_SA(1, 1), a3 + hstep, voffA);
;             PG8_MMA(1, 1, At, B1); PG8_BAR;
	s_setprio 1
	s_waitcnt lgkmcnt(3)
	v_mfma_f32_16x16x32_bf16 v[130:133], v[178:181], v[138:141], v[130:133]
	s_waitcnt lgkmcnt(1)
	v_mfma_f32_16x16x32_bf16 v[126:129], v[186:189], v[138:141], v[126:129]
	v_mfma_f32_16x16x32_bf16 v[102:105], v[178:181], v[146:149], v[102:105]
	v_mfma_f32_16x16x32_bf16 v[98:101], v[186:189], v[146:149], v[98:101]
	v_mfma_f32_16x16x32_bf16 v[86:89], v[178:181], v[154:157], v[86:89]
	v_mfma_f32_16x16x32_bf16 v[82:85], v[186:189], v[154:157], v[82:85]
	v_mfma_f32_16x16x32_bf16 v[70:73], v[178:181], v[162:165], v[70:73]
	v_mfma_f32_16x16x32_bf16 v[66:69], v[186:189], v[162:165], v[66:69]
	v_mfma_f32_16x16x32_bf16 v[130:133], v[182:185], v[142:145], v[130:133]
	s_waitcnt lgkmcnt(0)
	v_mfma_f32_16x16x32_bf16 v[126:129], v[190:193], v[142:145], v[126:129]
	v_mfma_f32_16x16x32_bf16 v[102:105], v[182:185], v[150:153], v[102:105]
	v_mfma_f32_16x16x32_bf16 v[98:101], v[190:193], v[150:153], v[98:101]
	v_mfma_f32_16x16x32_bf16 v[86:89], v[182:185], v[158:161], v[86:89]
	v_mfma_f32_16x16x32_bf16 v[82:85], v[190:193], v[158:161], v[82:85]
	v_mfma_f32_16x16x32_bf16 v[70:73], v[182:185], v[174:177], v[70:73]
	v_mfma_f32_16x16x32_bf16 v[66:69], v[190:193], v[174:177], v[66:69]
	s_setprio 0
	s_add_i32 m0, s46, 0xffffff80
	s_barrier
	ds_read_b128 v[138:141], v248 offset:49152
	ds_read_b128 v[142:145], v248 offset:50176
	ds_read_b128 v[146:149], v248 offset:51200
	ds_read_b128 v[150:153], v248 offset:52224
	ds_read_b128 v[154:157], v248 offset:53248
	ds_read_b128 v[158:161], v248 offset:54272
	ds_read_b128 v[162:165], v248 offset:55296
	ds_read_b128 v[174:177], v248 offset:56320
	global_load_lds_dwordx4 v198, s[68:69] offset:128
	s_add_i32 m0, s47, 0xffffff80
	s_nop 0
	global_load_lds_dwordx4 v196, s[68:69] offset:128
	s_barrier
	s_setprio 1
	s_waitcnt lgkmcnt(7)
	v_mfma_f32_16x16x32_bf16 v[62:65], v[106:109], v[138:141], v[62:65]
	v_mfma_f32_16x16x32_bf16 v[58:61], v[122:125], v[138:141], v[58:61]
	s_waitcnt lgkmcnt(5)
	v_mfma_f32_16x16x32_bf16 v[46:49], v[106:109], v[146:149], v[46:49]
	v_mfma_f32_16x16x32_bf16 v[42:45], v[122:125], v[146:149], v[42:45]
	s_waitcnt lgkmcnt(3)
	v_mfma_f32_16x16x32_bf16 v[30:33], v[106:109], v[154:157], v[30:33]
	v_mfma_f32_16x16x32_bf16 v[26:29], v[122:125], v[154:157], v[26:29]
	s_waitcnt lgkmcnt(1)
	v_mfma_f32_16x16x32_bf16 v[14:17], v[106:109], v[162:165], v[14:17]
	v_mfma_f32_16x16x32_bf16 v[10:13], v[122:125], v[162:165], v[10:13]
	v_mfma_f32_16x16x32_bf16 v[62:65], v[110:113], v[142:145], v[62:65]
	v_mfma_f32_16x16x32_bf16 v[58:61], v[134:137], v[142:145], v[58:61]
	v_mfma_f32_16x16x32_bf16 v[46:49], v[110:113], v[150:153], v[46:49]
	v_mfma_f32_16x16x32_bf16 v[42:45], v[134:137], v[150:153], v[42:45]
	v_mfma_f32_16x16x32_bf16 v[30:33], v[110:113], v[158:161], v[30:33]
	v_mfma_f32_16x16x32_bf16 v[26:29], v[134:137], v[158:161], v[26:29]
	s_waitcnt lgkmcnt(0)
	v_mfma_f32_16x16x32_bf16 v[14:17], v[110:113], v[174:177], v[14:17]
	v_mfma_f32_16x16x32_bf16 v[10:13], v[134:137], v[174:177], v[10:13]
	s_setprio 0
	s_barrier
	s_add_i32 s14, s14, s28
	s_add_u32 s16, s16, s26
	s_addc_u32 s17, s17, 0
	s_add_i32 m0, s14, 0xffffff80
	s_nop 0
	global_load_lds_dwordx4 v0, s[16:17] offset:128
	s_add_i32 m0, s14, 0x1f80
	s_nop 0
	global_load_lds_dwordx4 v194, s[16:17] offset:128
	s_add_u32 s68, s68, s26
	s_addc_u32 s69, s69, 0
	s_add_i32 m0, s48, 0xffffff80
	s_waitcnt vmcnt(6)
	s_barrier
	global_load_lds_dwordx4 v198, s[68:69] offset:128
	s_add_i32 m0, s49, 0xffffff80
	s_nop 0
	global_load_lds_dwordx4 v196, s[68:69] offset:128
	s_setprio 1
	v_mfma_f32_16x16x32_bf16 v[54:57], v[178:181], v[138:141], v[54:57]
	v_mfma_f32_16x16x32_bf16 v[50:53], v[186:189], v[138:141], v[50:53]
	v_mfma_f32_16x16x32_bf16 v[38:41], v[178:181], v[146:149], v[38:41]
	v_mfma_f32_16x16x32_bf16 v[34:37], v[186:189], v[146:149], v[34:37]
	v_mfma_f32_16x16x32_bf16 v[22:25], v[178:181], v[154:157], v[22:25]
	v_mfma_f32_16x16x32_bf16 v[18:21], v[186:189], v[154:157], v[18:21]
	v_mfma_f32_16x16x32_bf16 v[6:9], v[178:181], v[162:165], v[6:9]
	v_mfma_f32_16x16x32_bf16 v[2:5], v[186:189], v[162:165], v[2:5]
	v_mfma_f32_16x16x32_bf16 v[54:57], v[182:185], v[142:145], v[54:57]
	v_mfma_f32_16x16x32_bf16 v[50:53], v[190:193], v[142:145], v[50:53]
	v_mfma_f32_16x16x32_bf16 v[38:41], v[182:185], v[150:153], v[38:41]
	v_mfma_f32_16x16x32_bf16 v[34:37], v[190:193], v[150:153], v[34:37]
	v_mfma_f32_16x16x32_bf16 v[22:25], v[182:185], v[158:161], v[22:25]
	v_mfma_f32_16x16x32_bf16 v[18:21], v[190:193], v[158:161], v[18:21]
	v_mfma_f32_16x16x32_bf16 v[6:9], v[182:185], v[174:177], v[6:9]
	v_mfma_f32_16x16x32_bf16 v[2:5], v[190:193], v[174:177], v[2:5]
	s_setprio 0
	s_add_u32 s60, s60, 0x100
	s_addc_u32 s61, s61, 0
	s_add_u32 s64, s64, 0x100
	s_addc_u32 s65, s65, 0
	s_cmp_ge_u32 s67, s51
	s_mov_b32 s66, s67
	s_barrier
